# v36 + HP state-pass chunk loop: counted lgkmcnt waits at first use
# speedup vs baseline: 1.0019x; 1.0001x over previous
.LBB0_591:
	s_mul_i32 s10, s17, 37
	s_bfe_u32 s11, s10, 0x80008
	s_lshr_b32 s10, s10, 8
	s_sub_i32 s10, s17, s10
	s_bfe_u32 s10, s10, 0x70001
	s_add_i32 s10, s10, s11
	s_bfe_u32 s10, s10, 0x60002
	s_mul_i32 s10, s10, 7
	s_sub_i32 s10, s17, s10
	s_and_b32 s10, s10, 0xff
	s_mulk_i32 s10, 0x4400
	s_add_i32 s10, s10, 0
	s_add_i32 s11, s10, s37
	v_add_u32_e32 v62, s11, v80
	v_add3_u32 v62, v62, v81, v79
	v_add_u32_e32 v65, s10, v80
	v_add_u32_e32 v70, s10, v82
	ds_read_b64 v[62:63], v62 offset:12288
	v_add3_u32 v65, v65, v81, v79
	ds_read_b128 v[84:87], v70 offset:16384
	ds_read_b128 v[88:91], v70 offset:16448
	ds_read2st64_b64 v[92:95], v65 offset0:16 offset1:17
	ds_read2st64_b64 v[96:99], v65 offset0:18 offset1:19
	ds_read_b128 v[100:103], v70 offset:16512
	ds_read_b128 v[104:107], v70 offset:16576
	ds_read_b128 v[108:111], v70 offset:16640
	ds_read_b128 v[112:115], v70 offset:16704
	ds_read2st64_b64 v[116:119], v65 offset0:20 offset1:21
	ds_read2st64_b64 v[120:123], v65 offset0:22 offset1:23
	ds_read_b128 v[124:127], v70 offset:16768
	ds_read_b128 v[70:73], v70 offset:16832
	s_waitcnt lgkmcnt(11)
	v_pk_mul_f32 v[30:31], v[30:31], v[86:87]
	v_pk_mul_f32 v[28:29], v[28:29], v[84:85]
	v_pk_mul_f32 v[34:35], v[34:35], v[86:87]
	v_pk_mul_f32 v[32:33], v[32:33], v[84:85]
	s_waitcnt lgkmcnt(8)
	v_mov_b32_e32 v84, v96
	v_mov_b32_e32 v85, v97
	v_mov_b32_e32 v86, v64
	v_mov_b32_e32 v87, v64
	v_mov_b32_e32 v65, v64
	s_waitcnt lgkmcnt(6)
	v_pk_mul_f32 v[22:23], v[22:23], v[102:103]
	v_pk_mul_f32 v[20:21], v[20:21], v[100:101]
	v_pk_mul_f32 v[18:19], v[18:19], v[106:107]
	v_pk_mul_f32 v[16:17], v[16:17], v[104:105]
	v_mfma_f32_16x16x32_bf16 v[20:23], v[84:87], v[62:65], v[20:23]
	v_mov_b32_e32 v84, v98
	v_mov_b32_e32 v85, v99
	s_waitcnt lgkmcnt(5)
	v_pk_mul_f32 v[14:15], v[14:15], v[110:111]
	v_pk_mul_f32 v[12:13], v[12:13], v[108:109]
	v_mfma_f32_16x16x32_bf16 v[16:19], v[84:87], v[62:65], v[16:19]
	s_waitcnt lgkmcnt(3)
	v_mov_b32_e32 v84, v116
	v_mov_b32_e32 v85, v117
	v_pk_mul_f32 v[10:11], v[10:11], v[114:115]
	v_pk_mul_f32 v[8:9], v[8:9], v[112:113]
	v_mfma_f32_16x16x32_bf16 v[12:15], v[84:87], v[62:65], v[12:15]
	v_mov_b32_e32 v84, v118
	v_mov_b32_e32 v85, v119
	s_waitcnt lgkmcnt(1)
	v_pk_mul_f32 v[6:7], v[6:7], v[126:127]
	v_pk_mul_f32 v[4:5], v[4:5], v[124:125]
	v_mfma_f32_16x16x32_bf16 v[8:11], v[84:87], v[62:65], v[8:11]
	v_mov_b32_e32 v84, v120
	v_mov_b32_e32 v85, v121
	v_mov_b32_e32 v128, v92
	v_mov_b32_e32 v129, v93
	v_mov_b32_e32 v130, v64
	v_mov_b32_e32 v131, v64
	v_mov_b32_e32 v92, v94
	v_mov_b32_e32 v93, v95
	v_mov_b32_e32 v94, v64
	v_mov_b32_e32 v95, v64
	v_mfma_f32_16x16x32_bf16 v[4:7], v[84:87], v[62:65], v[4:7]
	v_mov_b32_e32 v84, v122
	v_mov_b32_e32 v85, v123
	v_pk_mul_f32 v[26:27], v[26:27], v[90:91]
	v_pk_mul_f32 v[24:25], v[24:25], v[88:89]
	s_waitcnt lgkmcnt(0)
	v_pk_mul_f32 v[2:3], v[2:3], v[72:73]
	v_pk_mul_f32 v[0:1], v[0:1], v[70:71]
	v_mfma_f32_16x16x32_bf16 v[28:31], v[128:131], v[62:65], v[28:31]
	s_add_i32 s17, s16, -5
	v_pk_mul_f32 v[38:39], v[38:39], v[90:91]
	v_pk_mul_f32 v[36:37], v[36:37], v[88:89]
	v_mfma_f32_16x16x32_bf16 v[24:27], v[92:95], v[62:65], v[24:27]
	v_mul_f32_e64 v42, v42, v102
	v_mul_f32_e64 v43, v43, v103
	v_pk_mul_f32 v[40:41], v[40:41], v[100:101]
	v_pk_mul_f32 v[46:47], v[46:47], v[106:107]
	v_mfma_f32_16x16x32_bf16 v[0:3], v[84:87], v[62:65], v[0:3]
	v_mul_f32_e64 v44, v44, v104
	v_mul_f32_e64 v45, v45, v105
	v_pk_mul_f32 v[50:51], v[50:51], v[110:111]
	v_pk_mul_f32 v[48:49], v[48:49], v[108:109]
	v_pk_mul_f32 v[54:55], v[54:55], v[114:115]
	v_pk_mul_f32 v[52:53], v[52:53], v[112:113]
	v_pk_mul_f32 v[58:59], v[58:59], v[126:127]
	v_pk_mul_f32 v[56:57], v[56:57], v[124:125]
	v_pk_mul_f32 v[68:69], v[68:69], v[72:73]
	s_cmp_eq_u32 s17, 16
	v_pk_mul_f32 v[66:67], v[66:67], v[70:71]
	s_cbranch_scc1 .LBB0_597
